# FoX main loop hand-scheduled + exact skipping of key blocks whose softmax weight is provably below 2^-64 of the row max (lower bound from 32 nearest keys)
# speedup vs baseline: 1.1057x; 1.1057x over previous
.LBB0_574:
	v_readfirstlane_b32 s2, v165
	s_nop 3
	s_lshr_b32 s2, s2, 6
	s_lshl_b32 s2, s2, 5
	s_lshl_b32 s3, s48, 8
	s_add_i32 s2, s2, s3
	s_add_i32 s20, s2, -32
	s_lshl_b32 s42, s20, 2
	s_mul_i32 s20, s20, 0x1e00
	s_add_u32 s20, s20, 0x7001200
	s_add_u32 s2, s28, s20
	s_addc_u32 s3, s29, 0
	v_and_b32_e32 v60, 31, v165
	v_mul_u32_u24_e32 v60, 0x1e00, v60
	v_bfe_u32 v61, v165, 5, 1
	v_lshl_add_u32 v60, v61, 4, v60
	v_add_u32_e32 v61, s42, v179
	global_load_dwordx4 v[64:67], v60, s[2:3] offset:0
	global_load_dwordx4 v[68:71], v60, s[2:3] offset:32
	global_load_dwordx4 v[72:75], v60, s[2:3] offset:64
	global_load_dwordx4 v[76:79], v60, s[2:3] offset:96
	ds_read_b128 v[32:35], v61
	ds_read_b128 v[36:39], v61 offset:32
	ds_read_b128 v[40:43], v61 offset:64
	ds_read_b128 v[44:47], v61 offset:96
	s_waitcnt lgkmcnt(0)
	s_waitcnt vmcnt(3)
	v_mfma_f32_32x32x16_bf16 v[32:47], v[64:67], v[96:99], v[32:47]
	s_waitcnt vmcnt(2)
	v_mfma_f32_32x32x16_bf16 v[32:47], v[68:71], v[100:103], v[32:47]
	s_waitcnt vmcnt(1)
	v_mfma_f32_32x32x16_bf16 v[32:47], v[72:75], v[104:107], v[32:47]
	s_waitcnt vmcnt(0)
	v_mfma_f32_32x32x16_bf16 v[32:47], v[76:79], v[108:111], v[32:47]
	s_nop 11
	v_max3_f32 v222, v32, v33, v34
	v_max3_f32 v222, v222, v35, v36
	v_max3_f32 v222, v222, v37, v38
	v_max3_f32 v222, v222, v39, v40
	v_max3_f32 v222, v222, v41, v42
	v_max3_f32 v222, v222, v43, v44
	v_max3_f32 v222, v222, v45, v46
	v_max_f32_e32 v222, v222, v47
	ds_bpermute_b32 v183, v180, v222
	s_waitcnt lgkmcnt(0)
	v_max_f32_e32 v183, v183, v183
	v_max_f32_e32 v182, v222, v183
	v_sub_f32_e32 v182, v182, v161
	v_add_f32_e32 v255, 0xc2800000, v182
.Lfox_top:
	v_lshl_add_u64 v[112:113], v[158:159], 0, s[36:37]
	v_add_co_u32_e32 v116, vcc, 0x70f1000, v112
	s_nop 1
	v_addc_co_u32_e32 v117, vcc, 0, v113, vcc
	v_add_co_u32_e32 v182, vcc, 0x7169000, v112
	s_nop 1
	v_addc_co_u32_e32 v183, vcc, 0, v113, vcc
	global_load_dwordx4 v[112:115], v[116:117], off offset:512
	s_nop 0
	global_load_dwordx4 v[116:119], v[116:117], off offset:1536
	global_load_dwordx4 v[120:123], v[182:183], off offset:512
	global_load_dwordx4 v[124:127], v[182:183], off offset:1536
	ds_read_b128 v[32:35], v179
	ds_read_b128 v[36:39], v179 offset:32
	ds_read_b128 v[40:43], v179 offset:64
	ds_read_b128 v[44:47], v179 offset:96
	ds_read_b128 v[48:51], v175 offset:16384
	ds_read_b128 v[52:55], v176 offset:16384
	ds_read_b128 v[56:59], v177 offset:16384
	ds_read_b128 v[60:63], v178 offset:16384
	ds_read_b128 v[80:83], v179 offset:128
	ds_read_b128 v[84:87], v179 offset:160
	ds_read_b128 v[88:91], v179 offset:192
	ds_read_b128 v[92:95], v179 offset:224
	s_waitcnt lgkmcnt(7)
	v_mfma_f32_32x32x16_bf16 v[32:47], v[48:51], v[96:99], v[32:47]
	ds_read_b128 v[64:67], v175 offset:20480
	s_waitcnt lgkmcnt(7)
	v_mfma_f32_32x32x16_bf16 v[32:47], v[52:55], v[100:103], v[32:47]
	ds_read_b128 v[68:71], v176 offset:20480
	s_waitcnt lgkmcnt(7)
	v_mfma_f32_32x32x16_bf16 v[32:47], v[56:59], v[104:107], v[32:47]
	ds_read_b128 v[72:75], v177 offset:20480
	s_waitcnt lgkmcnt(7)
	v_mfma_f32_32x32x16_bf16 v[32:47], v[60:63], v[108:111], v[32:47]
	ds_read_b128 v[76:79], v178 offset:20480
	ds_read_b128 v[48:51], v179 offset:256
	ds_read_b128 v[52:55], v179 offset:288
	ds_read_b128 v[56:59], v179 offset:320
	ds_read_b128 v[60:63], v179 offset:352
	s_waitcnt lgkmcnt(7)
	v_mfma_f32_32x32x16_bf16 v[80:95], v[64:67], v[96:99], v[80:95]
	ds_read_b128 v[202:205], v175 offset:24576
	s_waitcnt lgkmcnt(7)
	v_mfma_f32_32x32x16_bf16 v[80:95], v[68:71], v[100:103], v[80:95]
	ds_read_b128 v[206:209], v176 offset:24576
	s_waitcnt lgkmcnt(7)
	v_mfma_f32_32x32x16_bf16 v[80:95], v[72:75], v[104:107], v[80:95]
	ds_read_b128 v[210:213], v177 offset:24576
	s_waitcnt lgkmcnt(7)
	v_mfma_f32_32x32x16_bf16 v[80:95], v[76:79], v[108:111], v[80:95]
	ds_read_b128 v[214:217], v178 offset:24576
	ds_read_b128 v[64:67], v179 offset:384
	ds_read_b128 v[68:71], v179 offset:416
	ds_read_b128 v[72:75], v179 offset:448
	ds_read_b128 v[76:79], v179 offset:480
	ds_read_b128 v[218:221], v175 offset:28672
	v_max3_f32 v222, v32, v33, v34
	v_max3_f32 v222, v222, v35, v36
	v_max3_f32 v222, v222, v37, v38
	s_waitcnt lgkmcnt(8)
	v_mfma_f32_32x32x16_bf16 v[48:63], v[202:205], v[96:99], v[48:63]
	ds_read_b128 v[202:205], v176 offset:28672
	v_max3_f32 v222, v222, v39, v40
	v_max3_f32 v222, v222, v41, v42
	s_waitcnt lgkmcnt(8)
	v_mfma_f32_32x32x16_bf16 v[48:63], v[206:209], v[100:103], v[48:63]
	ds_read_b128 v[206:209], v177 offset:28672
	v_max3_f32 v222, v222, v43, v44
	v_max3_f32 v222, v222, v45, v46
	s_waitcnt lgkmcnt(8)
	v_mfma_f32_32x32x16_bf16 v[48:63], v[210:213], v[104:107], v[48:63]
	ds_read_b128 v[210:213], v178 offset:28672
	v_max3_f32 v222, v222, v47, v80
	v_max3_f32 v222, v222, v81, v82
	s_waitcnt lgkmcnt(8)
	v_mfma_f32_32x32x16_bf16 v[48:63], v[214:217], v[108:111], v[48:63]
	v_max3_f32 v222, v222, v83, v84
	v_max3_f32 v222, v222, v85, v86
	v_max3_f32 v222, v222, v87, v88
	s_waitcnt lgkmcnt(3)
	v_mfma_f32_32x32x16_bf16 v[64:79], v[218:221], v[96:99], v[64:79]
	v_max3_f32 v222, v222, v89, v90
	v_max3_f32 v222, v222, v91, v92
	s_waitcnt lgkmcnt(2)
	v_mfma_f32_32x32x16_bf16 v[64:79], v[202:205], v[100:103], v[64:79]
	v_max3_f32 v222, v222, v93, v94
	s_waitcnt lgkmcnt(1)
	v_mfma_f32_32x32x16_bf16 v[64:79], v[206:209], v[104:107], v[64:79]
	s_waitcnt lgkmcnt(0)
	v_mfma_f32_32x32x16_bf16 v[64:79], v[210:213], v[108:111], v[64:79]
	v_add_u32_e32 v254, 0xc000, v181
	v_max3_f32 v222, v222, v95, v48
	v_max3_f32 v222, v222, v49, v50
	v_max3_f32 v222, v222, v51, v52
	v_max3_f32 v222, v222, v53, v54
	v_max3_f32 v222, v222, v55, v56
	v_max3_f32 v222, v222, v57, v58
	v_max3_f32 v222, v222, v59, v60
	v_max3_f32 v222, v222, v61, v62
	s_nop 2
	v_max3_f32 v222, v222, v63, v64
	v_max3_f32 v222, v222, v65, v66
	v_max3_f32 v222, v222, v67, v68
	v_max3_f32 v222, v222, v69, v70
	v_max3_f32 v222, v222, v71, v72
	v_max3_f32 v222, v222, v73, v74
	v_max3_f32 v222, v222, v75, v76
	v_max3_f32 v222, v222, v77, v78
	v_max_f32_e32 v222, v222, v79
	ds_bpermute_b32 v183, v180, v222
	s_waitcnt lgkmcnt(0)
	v_max_f32_e32 v183, v183, v183
	v_max_f32_e32 v182, v222, v183
	v_sub_f32_e32 v182, v182, v161
	v_cmp_gt_f32_e32 vcc, v182, v255
	s_cbranch_vccz .Lfox_a_skip
	ds_read_b64_tr_b16 v[202:203], v254 offset:0
	ds_read_b64_tr_b16 v[204:205], v254 offset:1536
	ds_read_b64_tr_b16 v[206:207], v254 offset:64
	ds_read_b64_tr_b16 v[208:209], v254 offset:1600
	ds_read_b64_tr_b16 v[210:211], v254 offset:3072
	ds_read_b64_tr_b16 v[212:213], v254 offset:4608
	ds_read_b64_tr_b16 v[214:215], v254 offset:3136
	ds_read_b64_tr_b16 v[216:217], v254 offset:4672
	v_add_f32_e32 v183, 0x40c00000, v164
	v_cmp_gt_f32_e32 vcc, v182, v183
	s_cbranch_vccz .Lfox_a_pv
	v_max_f32_e32 v182, v182, v182
	v_max_f32_e32 v183, v164, v164
	v_max_f32_e32 v182, v183, v182
	v_sub_f32_e32 v164, v164, v182
	v_exp_f32_e32 v164, v164
	s_nop 0
	v_mul_f32_e32 v163, v163, v164
	v_pk_mul_f32 v[30:31], v[30:31], v[164:165] op_sel_hi:[1,0]
	v_pk_mul_f32 v[28:29], v[28:29], v[164:165] op_sel_hi:[1,0]
	v_pk_mul_f32 v[26:27], v[26:27], v[164:165] op_sel_hi:[1,0]
	v_pk_mul_f32 v[24:25], v[24:25], v[164:165] op_sel_hi:[1,0]
	v_pk_mul_f32 v[22:23], v[22:23], v[164:165] op_sel_hi:[1,0]
	v_pk_mul_f32 v[20:21], v[20:21], v[164:165] op_sel_hi:[1,0]
	v_pk_mul_f32 v[18:19], v[18:19], v[164:165] op_sel_hi:[1,0]
	v_pk_mul_f32 v[16:17], v[16:17], v[164:165] op_sel_hi:[1,0]
	v_pk_mul_f32 v[14:15], v[14:15], v[164:165] op_sel_hi:[1,0]
	v_pk_mul_f32 v[12:13], v[12:13], v[164:165] op_sel_hi:[1,0]
	v_pk_mul_f32 v[10:11], v[10:11], v[164:165] op_sel_hi:[1,0]
	v_pk_mul_f32 v[8:9], v[8:9], v[164:165] op_sel_hi:[1,0]
	v_pk_mul_f32 v[6:7], v[6:7], v[164:165] op_sel_hi:[1,0]
	v_pk_mul_f32 v[4:5], v[4:5], v[164:165] op_sel_hi:[1,0]
	v_pk_mul_f32 v[2:3], v[2:3], v[164:165] op_sel_hi:[1,0]
	v_pk_mul_f32 v[0:1], v[0:1], v[164:165] op_sel_hi:[1,0]
	v_mov_b32_e32 v164, v182
.Lfox_a_pv:
	v_sub_f32_e64 v222, -v161, v164
	v_add_f32_e32 v32, v32, v222
	v_add_f32_e32 v33, v33, v222
	v_add_f32_e32 v34, v34, v222
	v_add_f32_e32 v35, v35, v222
	v_add_f32_e32 v36, v36, v222
	v_add_f32_e32 v37, v37, v222
	v_add_f32_e32 v38, v38, v222
	v_add_f32_e32 v39, v39, v222
	v_exp_f32_e32 v32, v32
	v_exp_f32_e32 v33, v33
	v_exp_f32_e32 v34, v34
	v_exp_f32_e32 v35, v35
	v_exp_f32_e32 v36, v36
	v_exp_f32_e32 v37, v37
	v_exp_f32_e32 v38, v38
	v_exp_f32_e32 v39, v39
	v_add_f32_e32 v182, v32, v33
	v_add_f32_e32 v183, v34, v35
	v_add_f32_e32 v182, v182, v36
	v_add_f32_e32 v183, v183, v37
	v_add_f32_e32 v182, v182, v38
	v_add_f32_e32 v183, v183, v39
	v_cvt_pk_bf16_f32 v32, v32, v33
	v_cvt_pk_bf16_f32 v33, v34, v35
	v_cvt_pk_bf16_f32 v34, v36, v37
	v_cvt_pk_bf16_f32 v35, v38, v39
	s_waitcnt lgkmcnt(6)
	s_nop 0
	v_mfma_f32_32x32x16_bf16 v[16:31], v[202:205], v[32:35], v[16:31]
	v_add_f32_e32 v40, v40, v222
	v_add_f32_e32 v41, v41, v222
	v_add_f32_e32 v42, v42, v222
	v_add_f32_e32 v43, v43, v222
	v_add_f32_e32 v44, v44, v222
	v_add_f32_e32 v45, v45, v222
	v_add_f32_e32 v46, v46, v222
	v_add_f32_e32 v47, v47, v222
	v_exp_f32_e32 v40, v40
	v_exp_f32_e32 v41, v41
	v_exp_f32_e32 v42, v42
	v_exp_f32_e32 v43, v43
	v_exp_f32_e32 v44, v44
	v_exp_f32_e32 v45, v45
	v_exp_f32_e32 v46, v46
	v_exp_f32_e32 v47, v47
	s_waitcnt lgkmcnt(4)
	v_mfma_f32_32x32x16_bf16 v[0:15], v[206:209], v[32:35], v[0:15]
	ds_read_b64_tr_b16 v[202:203], v254 offset:6144
	ds_read_b64_tr_b16 v[204:205], v254 offset:7680
	ds_read_b64_tr_b16 v[206:207], v254 offset:6208
	ds_read_b64_tr_b16 v[208:209], v254 offset:7744
	v_add_f32_e32 v182, v182, v40
	v_add_f32_e32 v183, v183, v41
	v_add_f32_e32 v182, v182, v42
	v_add_f32_e32 v183, v183, v43
	v_add_f32_e32 v182, v182, v44
	v_add_f32_e32 v183, v183, v45
	v_add_f32_e32 v182, v182, v46
	v_add_f32_e32 v183, v183, v47
	v_cvt_pk_bf16_f32 v40, v40, v41
	v_cvt_pk_bf16_f32 v41, v42, v43
	v_cvt_pk_bf16_f32 v42, v44, v45
	v_cvt_pk_bf16_f32 v43, v46, v47
	s_waitcnt lgkmcnt(6)
	s_nop 0
	v_mfma_f32_32x32x16_bf16 v[16:31], v[210:213], v[40:43], v[16:31]
	v_add_f32_e32 v80, v80, v222
	v_add_f32_e32 v81, v81, v222
	v_add_f32_e32 v82, v82, v222
	v_add_f32_e32 v83, v83, v222
	v_add_f32_e32 v84, v84, v222
	v_add_f32_e32 v85, v85, v222
	v_add_f32_e32 v86, v86, v222
	v_add_f32_e32 v87, v87, v222
	v_exp_f32_e32 v80, v80
	v_exp_f32_e32 v81, v81
	v_exp_f32_e32 v82, v82
	v_exp_f32_e32 v83, v83
	v_exp_f32_e32 v84, v84
	v_exp_f32_e32 v85, v85
	v_exp_f32_e32 v86, v86
	v_exp_f32_e32 v87, v87
	s_waitcnt lgkmcnt(4)
	v_mfma_f32_32x32x16_bf16 v[0:15], v[214:217], v[40:43], v[0:15]
	ds_read_b64_tr_b16 v[210:211], v254 offset:9216
	ds_read_b64_tr_b16 v[212:213], v254 offset:10752
	ds_read_b64_tr_b16 v[214:215], v254 offset:9280
	ds_read_b64_tr_b16 v[216:217], v254 offset:10816
	v_add_f32_e32 v182, v182, v80
	v_add_f32_e32 v183, v183, v81
	v_add_f32_e32 v182, v182, v82
	v_add_f32_e32 v183, v183, v83
	v_add_f32_e32 v182, v182, v84
	v_add_f32_e32 v183, v183, v85
	v_add_f32_e32 v182, v182, v86
	v_add_f32_e32 v183, v183, v87
	v_cvt_pk_bf16_f32 v80, v80, v81
	v_cvt_pk_bf16_f32 v81, v82, v83
	v_cvt_pk_bf16_f32 v82, v84, v85
	v_cvt_pk_bf16_f32 v83, v86, v87
	s_waitcnt lgkmcnt(6)
	s_nop 0
	v_mfma_f32_32x32x16_bf16 v[16:31], v[202:205], v[80:83], v[16:31]
	v_add_f32_e32 v88, v88, v222
	v_add_f32_e32 v89, v89, v222
	v_add_f32_e32 v90, v90, v222
	v_add_f32_e32 v91, v91, v222
	v_add_f32_e32 v92, v92, v222
	v_add_f32_e32 v93, v93, v222
	v_add_f32_e32 v94, v94, v222
	v_add_f32_e32 v95, v95, v222
	v_exp_f32_e32 v88, v88
	v_exp_f32_e32 v89, v89
	v_exp_f32_e32 v90, v90
	v_exp_f32_e32 v91, v91
	v_exp_f32_e32 v92, v92
	v_exp_f32_e32 v93, v93
	v_exp_f32_e32 v94, v94
	v_exp_f32_e32 v95, v95
	s_waitcnt lgkmcnt(4)
	v_mfma_f32_32x32x16_bf16 v[0:15], v[206:209], v[80:83], v[0:15]
	ds_read_b64_tr_b16 v[202:203], v254 offset:12288
	ds_read_b64_tr_b16 v[204:205], v254 offset:13824
	ds_read_b64_tr_b16 v[206:207], v254 offset:12352
	ds_read_b64_tr_b16 v[208:209], v254 offset:13888
	v_add_f32_e32 v182, v182, v88
	v_add_f32_e32 v183, v183, v89
	v_add_f32_e32 v182, v182, v90
	v_add_f32_e32 v183, v183, v91
	v_add_f32_e32 v182, v182, v92
	v_add_f32_e32 v183, v183, v93
	v_add_f32_e32 v182, v182, v94
	v_add_f32_e32 v183, v183, v95
	v_cvt_pk_bf16_f32 v88, v88, v89
	v_cvt_pk_bf16_f32 v89, v90, v91
	v_cvt_pk_bf16_f32 v90, v92, v93
	v_cvt_pk_bf16_f32 v91, v94, v95
	s_waitcnt lgkmcnt(6)
	s_nop 0
	v_mfma_f32_32x32x16_bf16 v[16:31], v[210:213], v[88:91], v[16:31]
	v_add_f32_e32 v48, v48, v222
	v_add_f32_e32 v49, v49, v222
	v_add_f32_e32 v50, v50, v222
	v_add_f32_e32 v51, v51, v222
	v_add_f32_e32 v52, v52, v222
	v_add_f32_e32 v53, v53, v222
	v_add_f32_e32 v54, v54, v222
	v_add_f32_e32 v55, v55, v222
	v_exp_f32_e32 v48, v48
	v_exp_f32_e32 v49, v49
	v_exp_f32_e32 v50, v50
	v_exp_f32_e32 v51, v51
	v_exp_f32_e32 v52, v52
	v_exp_f32_e32 v53, v53
	v_exp_f32_e32 v54, v54
	v_exp_f32_e32 v55, v55
	s_waitcnt lgkmcnt(4)
	v_mfma_f32_32x32x16_bf16 v[0:15], v[214:217], v[88:91], v[0:15]
	ds_read_b64_tr_b16 v[210:211], v254 offset:15360
	ds_read_b64_tr_b16 v[212:213], v254 offset:16896
	ds_read_b64_tr_b16 v[214:215], v254 offset:15424
	ds_read_b64_tr_b16 v[216:217], v254 offset:16960
	v_add_f32_e32 v182, v182, v48
	v_add_f32_e32 v183, v183, v49
	v_add_f32_e32 v182, v182, v50
	v_add_f32_e32 v183, v183, v51
	v_add_f32_e32 v182, v182, v52
	v_add_f32_e32 v183, v183, v53
	v_add_f32_e32 v182, v182, v54
	v_add_f32_e32 v183, v183, v55
	v_cvt_pk_bf16_f32 v48, v48, v49
	v_cvt_pk_bf16_f32 v49, v50, v51
	v_cvt_pk_bf16_f32 v50, v52, v53
	v_cvt_pk_bf16_f32 v51, v54, v55
	s_waitcnt lgkmcnt(6)
	s_nop 0
	v_mfma_f32_32x32x16_bf16 v[16:31], v[202:205], v[48:51], v[16:31]
	v_add_f32_e32 v56, v56, v222
	v_add_f32_e32 v57, v57, v222
	v_add_f32_e32 v58, v58, v222
	v_add_f32_e32 v59, v59, v222
	v_add_f32_e32 v60, v60, v222
	v_add_f32_e32 v61, v61, v222
	v_add_f32_e32 v62, v62, v222
	v_add_f32_e32 v63, v63, v222
	v_exp_f32_e32 v56, v56
	v_exp_f32_e32 v57, v57
	v_exp_f32_e32 v58, v58
	v_exp_f32_e32 v59, v59
	v_exp_f32_e32 v60, v60
	v_exp_f32_e32 v61, v61
	v_exp_f32_e32 v62, v62
	v_exp_f32_e32 v63, v63
	s_waitcnt lgkmcnt(4)
	v_mfma_f32_32x32x16_bf16 v[0:15], v[206:209], v[48:51], v[0:15]
	ds_read_b64_tr_b16 v[202:203], v254 offset:18432
	ds_read_b64_tr_b16 v[204:205], v254 offset:19968
	ds_read_b64_tr_b16 v[206:207], v254 offset:18496
	ds_read_b64_tr_b16 v[208:209], v254 offset:20032
	v_add_f32_e32 v182, v182, v56
	v_add_f32_e32 v183, v183, v57
	v_add_f32_e32 v182, v182, v58
	v_add_f32_e32 v183, v183, v59
	v_add_f32_e32 v182, v182, v60
	v_add_f32_e32 v183, v183, v61
	v_add_f32_e32 v182, v182, v62
	v_add_f32_e32 v183, v183, v63
	v_cvt_pk_bf16_f32 v56, v56, v57
	v_cvt_pk_bf16_f32 v57, v58, v59
	v_cvt_pk_bf16_f32 v58, v60, v61
	v_cvt_pk_bf16_f32 v59, v62, v63
	s_waitcnt lgkmcnt(6)
	s_nop 0
	v_mfma_f32_32x32x16_bf16 v[16:31], v[210:213], v[56:59], v[16:31]
	v_add_f32_e32 v64, v64, v222
	v_add_f32_e32 v65, v65, v222
	v_add_f32_e32 v66, v66, v222
	v_add_f32_e32 v67, v67, v222
	v_add_f32_e32 v68, v68, v222
	v_add_f32_e32 v69, v69, v222
	v_add_f32_e32 v70, v70, v222
	v_add_f32_e32 v71, v71, v222
	v_exp_f32_e32 v64, v64
	v_exp_f32_e32 v65, v65
	v_exp_f32_e32 v66, v66
	v_exp_f32_e32 v67, v67
	v_exp_f32_e32 v68, v68
	v_exp_f32_e32 v69, v69
	v_exp_f32_e32 v70, v70
	v_exp_f32_e32 v71, v71
	s_waitcnt lgkmcnt(4)
	v_mfma_f32_32x32x16_bf16 v[0:15], v[214:217], v[56:59], v[0:15]
	ds_read_b64_tr_b16 v[210:211], v254 offset:21504
	ds_read_b64_tr_b16 v[212:213], v254 offset:23040
	ds_read_b64_tr_b16 v[214:215], v254 offset:21568
	ds_read_b64_tr_b16 v[216:217], v254 offset:23104
	v_add_f32_e32 v182, v182, v64
	v_add_f32_e32 v183, v183, v65
	v_add_f32_e32 v182, v182, v66
	v_add_f32_e32 v183, v183, v67
	v_add_f32_e32 v182, v182, v68
	v_add_f32_e32 v183, v183, v69
	v_add_f32_e32 v182, v182, v70
	v_add_f32_e32 v183, v183, v71
	v_cvt_pk_bf16_f32 v64, v64, v65
	v_cvt_pk_bf16_f32 v65, v66, v67
	v_cvt_pk_bf16_f32 v66, v68, v69
	v_cvt_pk_bf16_f32 v67, v70, v71
	s_waitcnt lgkmcnt(6)
	s_nop 0
	v_mfma_f32_32x32x16_bf16 v[16:31], v[202:205], v[64:67], v[16:31]
	v_add_f32_e32 v72, v72, v222
	v_add_f32_e32 v73, v73, v222
	v_add_f32_e32 v74, v74, v222
	v_add_f32_e32 v75, v75, v222
	v_add_f32_e32 v76, v76, v222
	v_add_f32_e32 v77, v77, v222
	v_add_f32_e32 v78, v78, v222
	v_add_f32_e32 v79, v79, v222
	v_exp_f32_e32 v72, v72
	v_exp_f32_e32 v73, v73
	v_exp_f32_e32 v74, v74
	v_exp_f32_e32 v75, v75
	v_exp_f32_e32 v76, v76
	v_exp_f32_e32 v77, v77
	v_exp_f32_e32 v78, v78
	v_exp_f32_e32 v79, v79
	s_waitcnt lgkmcnt(4)
	v_mfma_f32_32x32x16_bf16 v[0:15], v[206:209], v[64:67], v[0:15]
	v_add_f32_e32 v182, v182, v72
	v_add_f32_e32 v183, v183, v73
	v_add_f32_e32 v182, v182, v74
	v_add_f32_e32 v183, v183, v75
	v_add_f32_e32 v182, v182, v76
	v_add_f32_e32 v183, v183, v77
	v_add_f32_e32 v182, v182, v78
	v_add_f32_e32 v183, v183, v79
	v_cvt_pk_bf16_f32 v72, v72, v73
	v_cvt_pk_bf16_f32 v73, v74, v75
	v_cvt_pk_bf16_f32 v74, v76, v77
	v_cvt_pk_bf16_f32 v75, v78, v79
	s_waitcnt lgkmcnt(2)
	s_nop 0
	v_mfma_f32_32x32x16_bf16 v[16:31], v[210:213], v[72:75], v[16:31]
	s_waitcnt lgkmcnt(0)
	v_mfma_f32_32x32x16_bf16 v[0:15], v[214:217], v[72:75], v[0:15]
	v_add_f32_e32 v163, v163, v182
	v_add_f32_e32 v163, v163, v183
.Lfox_a_skip:
	s_waitcnt vmcnt(3)
	ds_write_b128 v147, v[112:115] offset:32768
	s_waitcnt vmcnt(1)
	ds_write_b128 v147, v[120:123] offset:40960
	v_add_u32_e32 v222, 0x12000, v153
	ds_write_b128 v222, v[116:119]
	s_waitcnt vmcnt(0)
	ds_write_b128 v222, v[124:127] offset:12288
	s_add_u32 s36, s36, 0xf0000
	s_addc_u32 s37, s37, 0
	s_waitcnt lgkmcnt(0)
	s_barrier
	v_lshl_add_u64 v[112:113], v[158:159], 0, s[36:37]
	v_add_co_u32_e32 v116, vcc, 0x70f1000, v112
	s_nop 1
	v_addc_co_u32_e32 v117, vcc, 0, v113, vcc
	v_add_co_u32_e32 v182, vcc, 0x7169000, v112
	s_nop 1
	v_addc_co_u32_e32 v183, vcc, 0, v113, vcc
	global_load_dwordx4 v[112:115], v[116:117], off offset:512
	s_nop 0
	global_load_dwordx4 v[116:119], v[116:117], off offset:1536
	global_load_dwordx4 v[120:123], v[182:183], off offset:512
	global_load_dwordx4 v[124:127], v[182:183], off offset:1536
	ds_read_b128 v[32:35], v179 offset:512
	ds_read_b128 v[36:39], v179 offset:544
	ds_read_b128 v[40:43], v179 offset:576
	ds_read_b128 v[44:47], v179 offset:608
	ds_read_b128 v[48:51], v175 offset:32768
	ds_read_b128 v[52:55], v176 offset:32768
	ds_read_b128 v[56:59], v177 offset:32768
	ds_read_b128 v[60:63], v178 offset:32768
	ds_read_b128 v[80:83], v179 offset:640
	ds_read_b128 v[84:87], v179 offset:672
	ds_read_b128 v[88:91], v179 offset:704
	ds_read_b128 v[92:95], v179 offset:736
	s_waitcnt lgkmcnt(7)
	v_mfma_f32_32x32x16_bf16 v[32:47], v[48:51], v[96:99], v[32:47]
	ds_read_b128 v[64:67], v175 offset:36864
	s_waitcnt lgkmcnt(7)
	v_mfma_f32_32x32x16_bf16 v[32:47], v[52:55], v[100:103], v[32:47]
	ds_read_b128 v[68:71], v176 offset:36864
	s_waitcnt lgkmcnt(7)
	v_mfma_f32_32x32x16_bf16 v[32:47], v[56:59], v[104:107], v[32:47]
	ds_read_b128 v[72:75], v177 offset:36864
	s_waitcnt lgkmcnt(7)
	v_mfma_f32_32x32x16_bf16 v[32:47], v[60:63], v[108:111], v[32:47]
	ds_read_b128 v[76:79], v178 offset:36864
	ds_read_b128 v[48:51], v179 offset:768
	ds_read_b128 v[52:55], v179 offset:800
	ds_read_b128 v[56:59], v179 offset:832
	ds_read_b128 v[60:63], v179 offset:864
	s_waitcnt lgkmcnt(7)
	v_mfma_f32_32x32x16_bf16 v[80:95], v[64:67], v[96:99], v[80:95]
	ds_read_b128 v[202:205], v175 offset:40960
	s_waitcnt lgkmcnt(7)
	v_mfma_f32_32x32x16_bf16 v[80:95], v[68:71], v[100:103], v[80:95]
	ds_read_b128 v[206:209], v176 offset:40960
	s_waitcnt lgkmcnt(7)
	v_mfma_f32_32x32x16_bf16 v[80:95], v[72:75], v[104:107], v[80:95]
	ds_read_b128 v[210:213], v177 offset:40960
	s_waitcnt lgkmcnt(7)
	v_mfma_f32_32x32x16_bf16 v[80:95], v[76:79], v[108:111], v[80:95]
	ds_read_b128 v[214:217], v178 offset:40960
	ds_read_b128 v[64:67], v179 offset:896
	ds_read_b128 v[68:71], v179 offset:928
	ds_read_b128 v[72:75], v179 offset:960
	ds_read_b128 v[76:79], v179 offset:992
	ds_read_b128 v[218:221], v175 offset:45056
	v_max3_f32 v222, v32, v33, v34
	v_max3_f32 v222, v222, v35, v36
	v_max3_f32 v222, v222, v37, v38
	s_waitcnt lgkmcnt(8)
	v_mfma_f32_32x32x16_bf16 v[48:63], v[202:205], v[96:99], v[48:63]
	ds_read_b128 v[202:205], v176 offset:45056
	v_max3_f32 v222, v222, v39, v40
	v_max3_f32 v222, v222, v41, v42
	s_waitcnt lgkmcnt(8)
	v_mfma_f32_32x32x16_bf16 v[48:63], v[206:209], v[100:103], v[48:63]
	ds_read_b128 v[206:209], v177 offset:45056
	v_max3_f32 v222, v222, v43, v44
	v_max3_f32 v222, v222, v45, v46
	s_waitcnt lgkmcnt(8)
	v_mfma_f32_32x32x16_bf16 v[48:63], v[210:213], v[104:107], v[48:63]
	ds_read_b128 v[210:213], v178 offset:45056
	v_max3_f32 v222, v222, v47, v80
	v_max3_f32 v222, v222, v81, v82
	s_waitcnt lgkmcnt(8)
	v_mfma_f32_32x32x16_bf16 v[48:63], v[214:217], v[108:111], v[48:63]
	v_max3_f32 v222, v222, v83, v84
	v_max3_f32 v222, v222, v85, v86
	v_max3_f32 v222, v222, v87, v88
	s_waitcnt lgkmcnt(3)
	v_mfma_f32_32x32x16_bf16 v[64:79], v[218:221], v[96:99], v[64:79]
	v_max3_f32 v222, v222, v89, v90
	v_max3_f32 v222, v222, v91, v92
	s_waitcnt lgkmcnt(2)
	v_mfma_f32_32x32x16_bf16 v[64:79], v[202:205], v[100:103], v[64:79]
	v_max3_f32 v222, v222, v93, v94
	s_waitcnt lgkmcnt(1)
	v_mfma_f32_32x32x16_bf16 v[64:79], v[206:209], v[104:107], v[64:79]
	s_waitcnt lgkmcnt(0)
	v_mfma_f32_32x32x16_bf16 v[64:79], v[210:213], v[108:111], v[64:79]
	v_add_u32_e32 v254, 0x12000, v181
	v_max3_f32 v222, v222, v95, v48
	v_max3_f32 v222, v222, v49, v50
	v_max3_f32 v222, v222, v51, v52
	v_max3_f32 v222, v222, v53, v54
	v_max3_f32 v222, v222, v55, v56
	v_max3_f32 v222, v222, v57, v58
	v_max3_f32 v222, v222, v59, v60
	v_max3_f32 v222, v222, v61, v62
	s_nop 2
	v_max3_f32 v222, v222, v63, v64
	v_max3_f32 v222, v222, v65, v66
	v_max3_f32 v222, v222, v67, v68
	v_max3_f32 v222, v222, v69, v70
	v_max3_f32 v222, v222, v71, v72
	v_max3_f32 v222, v222, v73, v74
	v_max3_f32 v222, v222, v75, v76
	v_max3_f32 v222, v222, v77, v78
	v_max_f32_e32 v222, v222, v79
	ds_bpermute_b32 v183, v180, v222
	s_waitcnt lgkmcnt(0)
	v_max_f32_e32 v183, v183, v183
	v_max_f32_e32 v182, v222, v183
	v_sub_f32_e32 v182, v182, v161
	v_cmp_gt_f32_e32 vcc, v182, v255
	s_cbranch_vccz .Lfox_b_skip
	ds_read_b64_tr_b16 v[202:203], v254 offset:0
	ds_read_b64_tr_b16 v[204:205], v254 offset:1536
	ds_read_b64_tr_b16 v[206:207], v254 offset:64
	ds_read_b64_tr_b16 v[208:209], v254 offset:1600
	ds_read_b64_tr_b16 v[210:211], v254 offset:3072
	ds_read_b64_tr_b16 v[212:213], v254 offset:4608
	ds_read_b64_tr_b16 v[214:215], v254 offset:3136
	ds_read_b64_tr_b16 v[216:217], v254 offset:4672
	v_add_f32_e32 v183, 0x40c00000, v164
	v_cmp_gt_f32_e32 vcc, v182, v183
	s_cbranch_vccz .Lfox_b_pv
	v_max_f32_e32 v182, v182, v182
	v_max_f32_e32 v183, v164, v164
	v_max_f32_e32 v182, v183, v182
	v_sub_f32_e32 v164, v164, v182
	v_exp_f32_e32 v164, v164
	s_nop 0
	v_mul_f32_e32 v163, v163, v164
	v_pk_mul_f32 v[30:31], v[30:31], v[164:165] op_sel_hi:[1,0]
	v_pk_mul_f32 v[28:29], v[28:29], v[164:165] op_sel_hi:[1,0]
	v_pk_mul_f32 v[26:27], v[26:27], v[164:165] op_sel_hi:[1,0]
	v_pk_mul_f32 v[24:25], v[24:25], v[164:165] op_sel_hi:[1,0]
	v_pk_mul_f32 v[22:23], v[22:23], v[164:165] op_sel_hi:[1,0]
	v_pk_mul_f32 v[20:21], v[20:21], v[164:165] op_sel_hi:[1,0]
	v_pk_mul_f32 v[18:19], v[18:19], v[164:165] op_sel_hi:[1,0]
	v_pk_mul_f32 v[16:17], v[16:17], v[164:165] op_sel_hi:[1,0]
	v_pk_mul_f32 v[14:15], v[14:15], v[164:165] op_sel_hi:[1,0]
	v_pk_mul_f32 v[12:13], v[12:13], v[164:165] op_sel_hi:[1,0]
	v_pk_mul_f32 v[10:11], v[10:11], v[164:165] op_sel_hi:[1,0]
	v_pk_mul_f32 v[8:9], v[8:9], v[164:165] op_sel_hi:[1,0]
	v_pk_mul_f32 v[6:7], v[6:7], v[164:165] op_sel_hi:[1,0]
	v_pk_mul_f32 v[4:5], v[4:5], v[164:165] op_sel_hi:[1,0]
	v_pk_mul_f32 v[2:3], v[2:3], v[164:165] op_sel_hi:[1,0]
	v_pk_mul_f32 v[0:1], v[0:1], v[164:165] op_sel_hi:[1,0]
	v_mov_b32_e32 v164, v182

.Lfox_b_skip:
	s_waitcnt vmcnt(3)
	ds_write_b128 v147, v[112:115] offset:16384
	s_waitcnt vmcnt(1)
	ds_write_b128 v147, v[120:123] offset:24576
	v_add_u32_e32 v222, 0xc000, v153
	ds_write_b128 v222, v[116:119]
	s_waitcnt vmcnt(0)
	ds_write_b128 v222, v[124:127] offset:12288
	s_add_u32 s36, s36, 0xf0000
	s_addc_u32 s37, s37, 0
	v_add_u32_e32 v179, 0x400, v179
	s_cmp_eq_u32 s80, s36
	s_waitcnt lgkmcnt(0)
	s_barrier
	s_cbranch_scc0 .Lfox_top

	.amdhsa_kernel _Z10fwd_kernel4Args
		.amdhsa_group_segment_fixed_size 0
		.amdhsa_private_segment_fixed_size 0
		.amdhsa_kernarg_size 368
		.amdhsa_user_sgpr_count 2
		.amdhsa_user_sgpr_dispatch_ptr 0
		.amdhsa_user_sgpr_queue_ptr 0
		.amdhsa_user_sgpr_kernarg_segment_ptr 1
		.amdhsa_user_sgpr_dispatch_id 0
		.amdhsa_user_sgpr_kernarg_preload_length 0
		.amdhsa_user_sgpr_kernarg_preload_offset 0
		.amdhsa_user_sgpr_private_segment_size 0
		.amdhsa_uses_dynamic_stack 0
		.amdhsa_enable_private_segment 0
		.amdhsa_system_sgpr_workgroup_id_x 1
		.amdhsa_system_sgpr_workgroup_id_y 0
		.amdhsa_system_sgpr_workgroup_id_z 0
		.amdhsa_system_sgpr_workgroup_info 0
		.amdhsa_system_vgpr_workitem_id 2
		.amdhsa_next_free_vgpr 256
		.amdhsa_next_free_sgpr 100
		.amdhsa_accum_offset 256
		.amdhsa_reserve_vcc 1
		.amdhsa_float_round_mode_32 0
		.amdhsa_float_round_mode_16_64 0
		.amdhsa_float_denorm_mode_32 3
		.amdhsa_float_denorm_mode_16_64 3
		.amdhsa_dx10_clamp 1
		.amdhsa_ieee_mode 1
		.amdhsa_fp16_overflow 0
		.amdhsa_tg_split 0
		.amdhsa_exception_fp_ieee_invalid_op 0
		.amdhsa_exception_fp_denorm_src 0
		.amdhsa_exception_fp_ieee_div_zero 0
		.amdhsa_exception_fp_ieee_overflow 0
		.amdhsa_exception_fp_ieee_underflow 0
		.amdhsa_exception_fp_ieee_inexact 0
		.amdhsa_exception_int_div_zero 0
	.end_amdhsa_kernel

amdhsa.kernels:
  - .agpr_count:     0
    .args:
      - .offset:         0
        .size:           112
        .value_kind:     by_value
      - .offset:         112
        .size:           4
        .value_kind:     hidden_block_count_x
      - .offset:         116
        .size:           4
        .value_kind:     hidden_block_count_y
      - .offset:         120
        .size:           4
        .value_kind:     hidden_block_count_z
      - .offset:         124
        .size:           2
        .value_kind:     hidden_group_size_x
      - .offset:         126
        .size:           2
        .value_kind:     hidden_group_size_y
      - .offset:         128
        .size:           2
        .value_kind:     hidden_group_size_z
      - .offset:         130
        .size:           2
        .value_kind:     hidden_remainder_x
      - .offset:         132
        .size:           2
        .value_kind:     hidden_remainder_y
      - .offset:         134
        .size:           2
        .value_kind:     hidden_remainder_z
      - .offset:         152
        .size:           8
        .value_kind:     hidden_global_offset_x
      - .offset:         160
        .size:           8
        .value_kind:     hidden_global_offset_y
      - .offset:         168
        .size:           8
        .value_kind:     hidden_global_offset_z
      - .offset:         176
        .size:           2
        .value_kind:     hidden_grid_dims
      - .offset:         200
        .size:           8
        .value_kind:     hidden_multigrid_sync_arg
      - .offset:         232
        .size:           4
        .value_kind:     hidden_dynamic_lds_size
    .group_segment_fixed_size: 0
    .kernarg_segment_align: 8
    .kernarg_segment_size: 368
    .language:       OpenCL C
    .language_version:
      - 2
      - 0
    .max_flat_workgroup_size: 512
    .name:           _Z10fwd_kernel4Args
    .private_segment_fixed_size: 0
    .sgpr_count:     106
    .sgpr_spill_count: 96
    .symbol:         _Z10fwd_kernel4Args.kd
    .uniform_work_group_size: 1
    .uses_dynamic_stack: false
    .vgpr_count:     256
    .vgpr_spill_count: 0
    .wavefront_size: 64
